# compress-GEMM-2 phase merged into the mid phase (workgroup pairs hand HID over via L2 write-back + counter; unit runs in the slack of the compress-GEMM-1 workgroups); the cmp2 phase and its grid barri
# baseline (speedup 1.0000x reference)
.Lc2m_start:
	s_waitcnt vmcnt(0)
	s_barrier
	v_cmp_eq_u32_e32 vcc, 0, v208
	s_and_saveexec_b64 s[2:3], vcc
	s_cbranch_execz .Lc2m_sync_done
	buffer_wbl2 sc1
	s_waitcnt vmcnt(0)
	v_readlane_b32 s4, v254, 4
	v_readlane_b32 s5, v254, 5
	s_lshr_b32 s6, s92, 1
	s_lshl_b32 s6, s6, 2
	s_add_u32 s4, s4, s6
	s_addc_u32 s5, s5, 0
	v_mov_b32_e32 v2, 0
	v_mov_b32_e32 v3, 1
	s_nop 2
	global_atomic_add v2, v3, s[4:5]
	s_bitcmp1_b32 s92, 0
	s_cbranch_scc1 .Lc2m_sync_done
	s_mov_b32 m0, 0
.Lc2m_spin:
	s_sleep 1
	global_load_dword v3, v2, s[4:5] sc1
	s_waitcnt vmcnt(0)
	v_readfirstlane_b32 s6, v3
	s_add_u32 m0, m0, 1
	s_cmp_ge_u32 s6, 2
	s_cbranch_scc1 .Lc2m_acq
	s_cmp_lt_u32 m0, 0x10000
	s_cbranch_scc1 .Lc2m_spin

.Lc2m_sync_done:
	s_or_b64 exec, exec, s[2:3]
	s_bitcmp1_b32 s92, 0
	s_cbranch_scc1 .LBB0_1209
	s_barrier
	s_mov_b64 s[2:3], s[58:59]
	v_mov_b32_e32 v1, v208
	v_mov_b32_e32 v2, v208
	v_ashrrev_i32_e32 v2, 1, v2
	s_load_dwordx2 s[4:5], s[2:3], 0xe0
	s_load_dwordx2 s[0:1], s[2:3], 0x40
	s_nop 0
	s_load_dwordx2 s[2:3], s[2:3], 0x68
	v_and_b32_e32 v132, 0xffffffe0, v2
	v_lshlrev_b32_e32 v3, 3, v1
	v_lshrrev_b32_e32 v2, 5, v2
	s_movk_i32 s6, 0x4080
	v_and_b32_e32 v134, 0x1f8, v3
	v_mul_lo_u32 v2, v2, s6
	v_add_u32_e32 v3, v134, v2
	s_waitcnt lgkmcnt(0)
	s_add_u32 s24, s4, 0x12de8800
	v_add_u32_e32 v5, 0x3e7c, v3
	s_addc_u32 s28, s5, 0
	v_or_b32_e32 v4, 4, v3
	v_mov_b32_e32 v135, v0
	v_cmp_ge_u32_e32 vcc, v5, v3
	v_add_u32_e32 v3, 0x3e80, v3
	s_add_u32 s29, s4, 0x1980000
	v_lshl_add_u64 v[136:137], s[2:3], 0, v[134:135]
	v_cmp_ge_u32_e64 s[2:3], v3, v4
	s_addc_u32 s30, s5, 0
	s_and_b64 s[10:11], vcc, s[2:3]
	s_add_u32 s12, s4, 0x13068800
	s_addc_u32 s13, s5, 0
	v_and_b32_e32 v1, 63, v1
	s_add_u32 s31, s4, 0x12fe8800
	v_mov_b32_e32 v133, v132
	v_lshl_add_u32 v135, v1, 3, v2
	s_addc_u32 s34, s5, 0
	s_lshr_b32 s39, s92, 1
	s_lshl_b32 s38, s39, 7
	s_branch .Lc2m_1264
.Lc2m_1263:
	s_barrier
	s_branch .Lc2m_exit

.Lc2m_exit:
	s_branch .LBB0_1209

.LBB0_1261:
	s_or_b64 exec, exec, s[0:1]
	v_readlane_b32 s0, v254, 54
	v_readlane_b32 s1, v254, 55
	s_mov_b64 s[2:3], s[58:59]
	v_mov_b32_e32 v1, v208
	s_waitcnt lgkmcnt(0)
	v_mov_b32_e32 v2, v208
	s_andn2_b64 vcc, exec, s[0:1]
	s_barrier
	.p2align 8
	s_branch .Lc2m_after
	s_cbranch_vccnz .LBB0_1315
	v_ashrrev_i32_e32 v2, 1, v2
	s_load_dwordx2 s[4:5], s[2:3], 0xe0
	s_load_dwordx2 s[0:1], s[2:3], 0x40
	s_nop 0
	s_load_dwordx2 s[2:3], s[2:3], 0x68
	v_and_b32_e32 v132, 0xffffffe0, v2
	v_lshlrev_b32_e32 v3, 3, v1
	v_lshrrev_b32_e32 v2, 5, v2
	s_movk_i32 s6, 0x4080
	v_and_b32_e32 v134, 0x1f8, v3
	v_mul_lo_u32 v2, v2, s6
	v_add_u32_e32 v3, v134, v2
	s_waitcnt lgkmcnt(0)
	s_add_u32 s24, s4, 0x12de8800
	v_add_u32_e32 v5, 0x3e7c, v3
	s_addc_u32 s28, s5, 0
	v_or_b32_e32 v4, 4, v3
	v_mov_b32_e32 v135, v0
	v_cmp_ge_u32_e32 vcc, v5, v3
	v_add_u32_e32 v3, 0x3e80, v3
	s_add_u32 s29, s4, 0x1980000
	v_lshl_add_u64 v[136:137], s[2:3], 0, v[134:135]
	v_cmp_ge_u32_e64 s[2:3], v3, v4
	s_addc_u32 s30, s5, 0
	s_and_b64 s[10:11], vcc, s[2:3]
	s_add_u32 s12, s4, 0x13068800
	s_addc_u32 s13, s5, 0
	v_and_b32_e32 v1, 63, v1
	s_add_u32 s31, s4, 0x12fe8800
	v_mov_b32_e32 v133, v132
	v_lshl_add_u32 v135, v1, 3, v2
	s_addc_u32 s34, s5, 0
	v_readlane_b32 s38, v255, 0
	s_mov_b32 s39, s92
	s_branch .LBB0_1264

.Lc2m_after:
	s_load_dwordx2 s[0:1], s[2:3], 0x10
	s_load_dwordx2 s[76:77], s[2:3], 0xe0
	s_waitcnt vmcnt(0)
	v_mov_b32_e32 v144, v208
	s_movk_i32 s20, 0x1020
	v_add_u32_e32 v9, 0x200, v144
	s_waitcnt lgkmcnt(0)
	s_add_u32 s18, s76, 0xddd8800
	v_ashrrev_i32_e32 v10, 4, v9
	v_add_u32_e32 v9, 0x300, v144
	s_addc_u32 s19, s77, 0
	v_ashrrev_i32_e32 v12, 4, v9
	v_max_i32_e32 v9, 0x104, v144
	s_add_u32 s86, s76, 0x14968800
	v_sub_u32_e32 v9, v9, v144
	s_addc_u32 s87, s77, 0
	v_add_u32_e32 v9, 0xff, v9
	v_ashrrev_i32_e32 v176, 6, v144
	s_add_u32 s16, s76, 0x1cae8800
	v_lshrrev_b32_e32 v11, 8, v9
	v_cmp_gt_i32_e64 s[4:5], s20, v144
	s_addc_u32 s17, s77, 0
	v_mul_lo_u32 v184, v176, s20
	v_add_u32_e32 v11, 1, v11
	v_cmp_lt_u32_e64 s[20:21], s53, v9
	s_add_u32 s43, s76, 0x20ae8800
	v_and_b32_e32 v193, 0x1fffffe, v11
	v_writelane_b32 v255, s20, 28
	s_addc_u32 s44, s77, 0
	v_and_b32_e32 v177, 31, v144
	v_writelane_b32 v255, s21, 29
	v_cmp_ne_u32_e64 s[20:21], v11, v193
	v_bfe_u32 v1, v144, 5, 1
	v_add_u32_e32 v145, 0x100, v144
	v_writelane_b32 v255, s20, 30
	s_add_u32 s94, s76, 0x13068800
	v_lshlrev_b32_e32 v4, 2, v1
	v_mul_u32_u24_e32 v7, 0x204, v177
	v_ashrrev_i32_e32 v6, 4, v144
	v_ashrrev_i32_e32 v8, 4, v145
	v_writelane_b32 v255, s21, 31
	v_lshlrev_b32_e32 v9, 2, v144
	s_addc_u32 s95, s77, 0
	s_mov_b32 s20, 0xb400
	v_and_b32_e32 v146, 63, v144
	v_lshlrev_b32_e32 v2, 3, v1
	v_lshlrev_b32_e32 v3, 4, v144
	v_lshlrev_b32_e32 v14, 4, v1
	v_lshlrev_b32_e32 v180, 3, v176
	s_movk_i32 s8, 0x110
	v_lshlrev_b32_e32 v1, 6, v1
	v_add_u32_e32 v195, 0xfc80, v9
	v_add_u32_e32 v196, 0xb400, v9
	v_add3_u32 v199, v7, v4, s20
	s_add_u32 s20, s76, 0x12fe8800
	v_ashrrev_i32_e32 v13, 31, v12
	v_ashrrev_i32_e32 v11, 31, v10
	v_ashrrev_i32_e32 v9, 31, v8
	v_ashrrev_i32_e32 v7, 31, v6
	v_lshlrev_b32_e32 v178, 2, v146
	v_and_b32_e32 v3, 0xf0, v3
	v_mul_u32_u24_e32 v5, 0x110, v177
	v_or_b32_e32 v148, 64, v146
	v_lshlrev_b32_e32 v15, 9, v176
	v_mul_lo_u32 v16, v6, s8
	v_mul_lo_u32 v17, v8, s8
	v_mul_lo_u32 v18, v10, s8
	v_mul_lo_u32 v19, v12, s8
	v_or_b32_e32 v185, 1, v180
	v_sub_u32_e32 v198, v177, v1
	v_and_b32_e32 v1, 15, v144
	s_addc_u32 s21, s77, 0
	v_lshlrev_b64 v[12:13], 8, v[12:13]
	v_lshlrev_b64 v[10:11], 8, v[10:11]
	v_lshlrev_b64 v[8:9], 8, v[8:9]
	v_lshlrev_b64 v[6:7], 8, v[6:7]
	v_cmp_gt_i32_e64 s[2:3], s56, v144
	v_mul_lo_u32 v179, v176, s56
	s_mov_b32 s42, 0
	v_cmp_eq_u32_e64 s[6:7], 0, v146
	v_or_b32_e32 v181, v178, v15
	v_lshlrev_b32_e32 v182, 6, v146
	v_lshlrev_b32_e32 v183, 6, v148
	s_movk_i32 s97, 0x110
	v_cmp_gt_u32_e64 s[8:9], 64, v144
	v_cmp_eq_u32_e64 s[10:11], 1, v176
	v_cmp_eq_u32_e64 s[12:13], 2, v176
	v_cmp_eq_u32_e64 s[14:15], 3, v176
	v_mul_lo_u32 v186, v185, s56
	v_or_b32_e32 v187, 2, v180
	v_or_b32_e32 v188, 3, v180
	v_or_b32_e32 v189, 4, v180
	v_or_b32_e32 v190, 5, v180
	v_or_b32_e32 v191, 6, v180
	v_or_b32_e32 v192, 7, v180
	v_lshl_add_u32 v194, v193, 8, v144
	v_mov_b32_e32 v147, v146
	v_mov_b32_e32 v149, v148
	v_add_u32_e32 v197, 0xffffff00, v144
	v_lshlrev_b32_e32 v150, 4, v1
	v_mov_b32_e32 v151, v0
	v_lshl_add_u64 v[152:153], s[20:21], 0, v[12:13]
	v_lshl_add_u64 v[154:155], s[20:21], 0, v[10:11]
	v_lshl_add_u64 v[156:157], s[20:21], 0, v[8:9]
	v_lshl_add_u64 v[158:159], s[20:21], 0, v[6:7]
	v_add_u32_e32 v200, 0xf480, v15
	v_lshlrev_b32_e32 v160, 1, v2
	v_lshlrev_b32_e32 v162, 2, v4
	v_add_u32_e32 v201, v3, v16
	v_add_u32_e32 v202, v3, v17
	v_add_u32_e32 v203, v3, v18
	v_add_u32_e32 v204, v3, v19
	v_add_u32_e32 v205, v5, v14
	s_mov_b32 s34, s92
	s_branch .LBB0_1370
